# v6: v5 + gridDim==256 guards on the W_out half-unit paths
# speedup vs baseline: 1.0038x; 1.0038x over previous
.LBB0_958:
	v_add_u32_e32 v164, s82, v237
	ds_read_b128 v[56:59], v239
	ds_read_b128 v[60:63], v239 offset:1024
	ds_read_b128 v[144:147], v239 offset:2048
	ds_read_b128 v[148:151], v239 offset:3072
	ds_read_b128 v[152:155], v164
	ds_read_b128 v[156:159], v164 offset:1024
	ds_read_b128 v[160:163], v164 offset:2048
	ds_read_b128 v[164:167], v164 offset:3072
	s_cmp_eq_u32 s7, 12
	v_lshl_add_u64 v[168:169], v[44:45], 0, s[36:37]
	s_cselect_b64 vcc, -1, 0
	v_cndmask_b32_e32 v241, v169, v41, vcc
	v_cndmask_b32_e32 v240, v168, v40, vcc
	v_cndmask_b32_e32 v243, v47, v43, vcc
	v_cndmask_b32_e32 v242, v46, v42, vcc
	v_lshl_add_u64 v[244:245], v[44:45], 0, v[208:209]
	s_add_i32 m0, s69, 0xc000
	ds_read_b128 v[168:171], v238
	ds_read_b128 v[172:175], v238 offset:1024
	ds_read_b128 v[176:179], v238 offset:2048
	ds_read_b128 v[180:183], v238 offset:3072
	ds_read_b128 v[218:221], v238 offset:4096
	ds_read_b128 v[222:225], v238 offset:5120
	ds_read_b128 v[226:229], v238 offset:6144
	ds_read_b128 v[230:233], v238 offset:7168
	global_load_lds_dwordx4 v[244:245], off
	v_lshl_add_u64 v[244:245], v[44:45], 0, v[210:211]
	s_add_i32 m0, s69, 0xe000
	s_nop 0
	global_load_lds_dwordx4 v[244:245], off
	s_waitcnt vmcnt(8)
	s_waitcnt lgkmcnt(0)
	s_barrier
	s_setprio 1
	s_waitcnt lgkmcnt(0)
	v_mfma_f32_16x16x32_bf16 v[140:143], v[56:59], v[168:171], v[140:143]
	v_mfma_f32_16x16x32_bf16 v[136:139], v[144:147], v[168:171], v[136:139]
	v_mfma_f32_16x16x32_bf16 v[124:127], v[56:59], v[176:179], v[124:127]
	v_mfma_f32_16x16x32_bf16 v[120:123], v[144:147], v[176:179], v[120:123]
	v_mfma_f32_16x16x32_bf16 v[108:111], v[56:59], v[218:221], v[108:111]
	v_mfma_f32_16x16x32_bf16 v[104:107], v[144:147], v[218:221], v[104:107]
	v_mfma_f32_16x16x32_bf16 v[92:95], v[56:59], v[226:229], v[92:95]
	v_mfma_f32_16x16x32_bf16 v[88:91], v[144:147], v[226:229], v[88:91]
	v_mfma_f32_16x16x32_bf16 v[140:143], v[60:63], v[172:175], v[140:143]
	v_mfma_f32_16x16x32_bf16 v[136:139], v[148:151], v[172:175], v[136:139]
	v_mfma_f32_16x16x32_bf16 v[124:127], v[60:63], v[180:183], v[124:127]
	v_mfma_f32_16x16x32_bf16 v[120:123], v[148:151], v[180:183], v[120:123]
	v_mfma_f32_16x16x32_bf16 v[108:111], v[60:63], v[222:225], v[108:111]
	v_mfma_f32_16x16x32_bf16 v[104:107], v[148:151], v[222:225], v[104:107]
	v_mfma_f32_16x16x32_bf16 v[92:95], v[60:63], v[230:233], v[92:95]
	v_mfma_f32_16x16x32_bf16 v[88:91], v[148:151], v[230:233], v[88:91]
	s_setprio 0
	s_setprio 1
	v_mfma_f32_16x16x32_bf16 v[132:135], v[152:155], v[168:171], v[132:135]
	v_mfma_f32_16x16x32_bf16 v[128:131], v[160:163], v[168:171], v[128:131]
	v_mfma_f32_16x16x32_bf16 v[116:119], v[152:155], v[176:179], v[116:119]
	v_mfma_f32_16x16x32_bf16 v[112:115], v[160:163], v[176:179], v[112:115]
	v_mfma_f32_16x16x32_bf16 v[100:103], v[152:155], v[218:221], v[100:103]
	v_mfma_f32_16x16x32_bf16 v[96:99], v[160:163], v[218:221], v[96:99]
	v_mfma_f32_16x16x32_bf16 v[84:87], v[152:155], v[226:229], v[84:87]
	v_mfma_f32_16x16x32_bf16 v[80:83], v[160:163], v[226:229], v[80:83]
	v_mfma_f32_16x16x32_bf16 v[132:135], v[156:159], v[172:175], v[132:135]
	v_mfma_f32_16x16x32_bf16 v[128:131], v[164:167], v[172:175], v[128:131]
	v_mfma_f32_16x16x32_bf16 v[116:119], v[156:159], v[180:183], v[116:119]
	v_mfma_f32_16x16x32_bf16 v[112:115], v[164:167], v[180:183], v[112:115]
	v_mfma_f32_16x16x32_bf16 v[100:103], v[156:159], v[222:225], v[100:103]
	v_mfma_f32_16x16x32_bf16 v[96:99], v[164:167], v[222:225], v[96:99]
	v_mfma_f32_16x16x32_bf16 v[84:87], v[156:159], v[230:233], v[84:87]
	v_mfma_f32_16x16x32_bf16 v[80:83], v[164:167], v[230:233], v[80:83]
	s_setprio 0
	s_barrier
	s_add_i32 s8, s81, s68
	v_lshl_add_u64 v[244:245], v[242:243], 0, v[192:193]
	s_mov_b32 m0, s8
	ds_read_b128 v[168:171], v238 offset:16384
	ds_read_b128 v[172:175], v238 offset:17408
	ds_read_b128 v[176:179], v238 offset:18432
	ds_read_b128 v[180:183], v238 offset:19456
	ds_read_b128 v[218:221], v238 offset:20480
	ds_read_b128 v[222:225], v238 offset:21504
	ds_read_b128 v[226:229], v238 offset:22528
	ds_read_b128 v[230:233], v238 offset:23552
	global_load_lds_dwordx4 v[244:245], off
	v_lshl_add_u64 v[246:247], v[242:243], 0, v[196:197]
	s_add_i32 m0, s8, 0x2000
	v_lshl_add_u64 v[248:249], v[242:243], 0, s[16:17]
	s_add_i32 s8, s82, s68
	global_load_lds_dwordx4 v[246:247], off
	v_lshl_add_u64 v[250:251], v[248:249], 0, v[192:193]
	s_mov_b32 m0, s8
	v_lshl_add_u64 v[248:249], v[248:249], 0, v[196:197]
	global_load_lds_dwordx4 v[250:251], off
	s_add_i32 m0, s8, 0x2000
	v_lshl_add_u64 v[250:251], v[240:241], 0, v[194:195]
	global_load_lds_dwordx4 v[248:249], off
	v_lshl_add_u64 v[248:249], v[240:241], 0, v[190:191]
	s_mov_b32 m0, s69
	s_nop 0
	global_load_lds_dwordx4 v[248:249], off
	s_mov_b32 m0, s70
	s_nop 0
	global_load_lds_dwordx4 v[250:251], off
	s_waitcnt vmcnt(8)
	s_waitcnt lgkmcnt(0)
	s_barrier
	s_setprio 1
	s_waitcnt lgkmcnt(0)
	s_cmp_eq_u32 s84, 2
	s_cbranch_scc0 .Lwo_half_full_a
	s_cmp_eq_u32 s79, 0x100
	s_cbranch_scc1 .Lwo_half_skip_a
.Lwo_half_full_a:
	v_mfma_f32_16x16x32_bf16 v[76:79], v[56:59], v[168:171], v[76:79]
	v_mfma_f32_16x16x32_bf16 v[72:75], v[144:147], v[168:171], v[72:75]
	v_mfma_f32_16x16x32_bf16 v[52:55], v[56:59], v[176:179], v[52:55]
	v_mfma_f32_16x16x32_bf16 v[48:51], v[144:147], v[176:179], v[48:51]
	v_mfma_f32_16x16x32_bf16 v[28:31], v[56:59], v[218:221], v[28:31]
	v_mfma_f32_16x16x32_bf16 v[24:27], v[144:147], v[218:221], v[24:27]
	v_mfma_f32_16x16x32_bf16 v[12:15], v[56:59], v[226:229], v[12:15]
	v_mfma_f32_16x16x32_bf16 v[8:11], v[144:147], v[226:229], v[8:11]
	v_mfma_f32_16x16x32_bf16 v[76:79], v[60:63], v[172:175], v[76:79]
	v_mfma_f32_16x16x32_bf16 v[72:75], v[148:151], v[172:175], v[72:75]
	v_mfma_f32_16x16x32_bf16 v[52:55], v[60:63], v[180:183], v[52:55]
	v_mfma_f32_16x16x32_bf16 v[48:51], v[148:151], v[180:183], v[48:51]
	v_mfma_f32_16x16x32_bf16 v[28:31], v[60:63], v[222:225], v[28:31]
	v_mfma_f32_16x16x32_bf16 v[24:27], v[148:151], v[222:225], v[24:27]
	v_mfma_f32_16x16x32_bf16 v[12:15], v[60:63], v[230:233], v[12:15]
	v_mfma_f32_16x16x32_bf16 v[8:11], v[148:151], v[230:233], v[8:11]
	s_setprio 0
	s_setprio 1
	v_mfma_f32_16x16x32_bf16 v[36:39], v[152:155], v[176:179], v[36:39]
	v_mfma_f32_16x16x32_bf16 v[32:35], v[160:163], v[176:179], v[32:35]
	v_mfma_f32_16x16x32_bf16 v[20:23], v[152:155], v[218:221], v[20:23]
	v_mfma_f32_16x16x32_bf16 v[16:19], v[160:163], v[218:221], v[16:19]
	v_mfma_f32_16x16x32_bf16 v[4:7], v[152:155], v[226:229], v[4:7]
	v_mfma_f32_16x16x32_bf16 v[0:3], v[160:163], v[226:229], v[0:3]
	v_mfma_f32_16x16x32_bf16 v[56:59], v[152:155], v[168:171], v[68:71]
	v_mfma_f32_16x16x32_bf16 v[60:63], v[160:163], v[168:171], v[64:67]
	v_mfma_f32_16x16x32_bf16 v[36:39], v[156:159], v[180:183], v[36:39]
	v_mfma_f32_16x16x32_bf16 v[32:35], v[164:167], v[180:183], v[32:35]
	v_mfma_f32_16x16x32_bf16 v[20:23], v[156:159], v[222:225], v[20:23]
	v_mfma_f32_16x16x32_bf16 v[16:19], v[164:167], v[222:225], v[16:19]
	v_mfma_f32_16x16x32_bf16 v[4:7], v[156:159], v[230:233], v[4:7]
	v_mfma_f32_16x16x32_bf16 v[0:3], v[164:167], v[230:233], v[0:3]
	v_mfma_f32_16x16x32_bf16 v[56:59], v[156:159], v[172:175], v[56:59]
	v_mfma_f32_16x16x32_bf16 v[60:63], v[164:167], v[172:175], v[60:63]
.Lwo_half_skip_a:
	s_setprio 0
	s_barrier
	s_add_i32 s8, 0, 0x18000
	s_add_i32 s9, 0, 0x1c000
	v_add_u32_e32 v148, s8, v237
	v_add_u32_e32 v164, s9, v237
	ds_read_b128 v[64:67], v148
	ds_read_b128 v[68:71], v148 offset:1024
	ds_read_b128 v[144:147], v148 offset:2048
	ds_read_b128 v[148:151], v148 offset:3072
	ds_read_b128 v[152:155], v164
	ds_read_b128 v[156:159], v164 offset:1024
	ds_read_b128 v[160:163], v164 offset:2048
	ds_read_b128 v[164:167], v164 offset:3072
	v_lshl_add_u64 v[240:241], v[240:241], 0, s[16:17]
	s_mov_b32 m0, s71
	v_lshl_add_u64 v[252:253], v[240:241], 0, v[190:191]
	ds_read_b128 v[168:171], v238 offset:32768
	ds_read_b128 v[172:175], v238 offset:33792
	ds_read_b128 v[176:179], v238 offset:34816
	ds_read_b128 v[180:183], v238 offset:35840
	ds_read_b128 v[218:221], v238 offset:36864
	ds_read_b128 v[222:225], v238 offset:37888
	ds_read_b128 v[226:229], v238 offset:38912
	ds_read_b128 v[230:233], v238 offset:39936
	global_load_lds_dwordx4 v[252:253], off
	v_lshl_add_u64 v[240:241], v[240:241], 0, v[194:195]
	s_mov_b32 m0, s72
	s_nop 0
	global_load_lds_dwordx4 v[240:241], off
	s_waitcnt vmcnt(8)
	s_waitcnt lgkmcnt(0)
	s_barrier
	s_setprio 1
	s_waitcnt lgkmcnt(0)
	v_mfma_f32_16x16x32_bf16 v[140:143], v[64:67], v[168:171], v[140:143]
	v_mfma_f32_16x16x32_bf16 v[136:139], v[144:147], v[168:171], v[136:139]
	v_mfma_f32_16x16x32_bf16 v[124:127], v[64:67], v[176:179], v[124:127]
	v_mfma_f32_16x16x32_bf16 v[120:123], v[144:147], v[176:179], v[120:123]
	v_mfma_f32_16x16x32_bf16 v[108:111], v[64:67], v[218:221], v[108:111]
	v_mfma_f32_16x16x32_bf16 v[104:107], v[144:147], v[218:221], v[104:107]
	v_mfma_f32_16x16x32_bf16 v[92:95], v[64:67], v[226:229], v[92:95]
	v_mfma_f32_16x16x32_bf16 v[88:91], v[144:147], v[226:229], v[88:91]
	v_mfma_f32_16x16x32_bf16 v[140:143], v[68:71], v[172:175], v[140:143]
	v_mfma_f32_16x16x32_bf16 v[136:139], v[148:151], v[172:175], v[136:139]
	v_mfma_f32_16x16x32_bf16 v[124:127], v[68:71], v[180:183], v[124:127]
	v_mfma_f32_16x16x32_bf16 v[120:123], v[148:151], v[180:183], v[120:123]
	v_mfma_f32_16x16x32_bf16 v[108:111], v[68:71], v[222:225], v[108:111]
	v_mfma_f32_16x16x32_bf16 v[104:107], v[148:151], v[222:225], v[104:107]
	v_mfma_f32_16x16x32_bf16 v[92:95], v[68:71], v[230:233], v[92:95]
	v_mfma_f32_16x16x32_bf16 v[88:91], v[148:151], v[230:233], v[88:91]
	s_setprio 0
	s_setprio 1
	v_mfma_f32_16x16x32_bf16 v[132:135], v[152:155], v[168:171], v[132:135]
	v_mfma_f32_16x16x32_bf16 v[128:131], v[160:163], v[168:171], v[128:131]
	v_mfma_f32_16x16x32_bf16 v[116:119], v[152:155], v[176:179], v[116:119]
	v_mfma_f32_16x16x32_bf16 v[112:115], v[160:163], v[176:179], v[112:115]
	v_mfma_f32_16x16x32_bf16 v[100:103], v[152:155], v[218:221], v[100:103]
	v_mfma_f32_16x16x32_bf16 v[96:99], v[160:163], v[218:221], v[96:99]
	v_mfma_f32_16x16x32_bf16 v[84:87], v[152:155], v[226:229], v[84:87]
	v_mfma_f32_16x16x32_bf16 v[80:83], v[160:163], v[226:229], v[80:83]
	v_mfma_f32_16x16x32_bf16 v[132:135], v[156:159], v[172:175], v[132:135]
	v_mfma_f32_16x16x32_bf16 v[128:131], v[164:167], v[172:175], v[128:131]
	v_mfma_f32_16x16x32_bf16 v[116:119], v[156:159], v[180:183], v[116:119]
	v_mfma_f32_16x16x32_bf16 v[112:115], v[164:167], v[180:183], v[112:115]
	v_mfma_f32_16x16x32_bf16 v[100:103], v[156:159], v[222:225], v[100:103]
	v_mfma_f32_16x16x32_bf16 v[96:99], v[164:167], v[222:225], v[96:99]
	v_mfma_f32_16x16x32_bf16 v[84:87], v[156:159], v[230:233], v[84:87]
	v_mfma_f32_16x16x32_bf16 v[80:83], v[164:167], v[230:233], v[80:83]
	s_setprio 0
	s_barrier
	s_add_i32 s8, s8, s68
	v_lshl_add_u64 v[240:241], v[244:245], 0, s[26:27]
	s_mov_b32 m0, s8
	ds_read_b128 v[168:171], v238 offset:49152
	ds_read_b128 v[172:175], v238 offset:50176
	ds_read_b128 v[176:179], v238 offset:51200
	ds_read_b128 v[180:183], v238 offset:52224
	ds_read_b128 v[218:221], v238 offset:53248
	ds_read_b128 v[222:225], v238 offset:54272
	ds_read_b128 v[226:229], v238 offset:55296
	ds_read_b128 v[230:233], v238 offset:56320
	global_load_lds_dwordx4 v[240:241], off
	v_lshl_add_u64 v[240:241], v[246:247], 0, s[26:27]
	s_add_i32 m0, s8, 0x2000
	s_add_i32 s8, s9, s68
	global_load_lds_dwordx4 v[240:241], off
	v_lshl_add_u64 v[240:241], v[242:243], 0, s[28:29]
	v_lshl_add_u64 v[242:243], v[240:241], 0, v[192:193]
	s_mov_b32 m0, s8
	v_lshl_add_u64 v[240:241], v[240:241], 0, v[196:197]
	global_load_lds_dwordx4 v[242:243], off
	s_add_i32 m0, s8, 0x2000
	s_nop 0
	global_load_lds_dwordx4 v[240:241], off
	v_lshl_add_u64 v[240:241], v[248:249], 0, s[26:27]
	s_mov_b32 m0, s73
	s_nop 0
	global_load_lds_dwordx4 v[240:241], off
	v_lshl_add_u64 v[240:241], v[250:251], 0, s[26:27]
	s_mov_b32 m0, s74
	s_nop 0
	global_load_lds_dwordx4 v[240:241], off
	s_waitcnt vmcnt(8)
	s_waitcnt lgkmcnt(0)
	s_barrier
	s_setprio 1
	s_waitcnt lgkmcnt(0)
	s_cmp_eq_u32 s84, 2
	s_cbranch_scc0 .Lwo_half_full_b
	s_cmp_eq_u32 s79, 0x100
	s_cbranch_scc1 .Lwo_half_skip_b
.Lwo_half_full_b:
	v_mfma_f32_16x16x32_bf16 v[76:79], v[64:67], v[168:171], v[76:79]
	v_mfma_f32_16x16x32_bf16 v[72:75], v[144:147], v[168:171], v[72:75]
	v_mfma_f32_16x16x32_bf16 v[52:55], v[64:67], v[176:179], v[52:55]
	v_mfma_f32_16x16x32_bf16 v[48:51], v[144:147], v[176:179], v[48:51]
	v_mfma_f32_16x16x32_bf16 v[28:31], v[64:67], v[218:221], v[28:31]
	v_mfma_f32_16x16x32_bf16 v[24:27], v[144:147], v[218:221], v[24:27]
	v_mfma_f32_16x16x32_bf16 v[12:15], v[64:67], v[226:229], v[12:15]
	v_mfma_f32_16x16x32_bf16 v[8:11], v[144:147], v[226:229], v[8:11]
	v_mfma_f32_16x16x32_bf16 v[76:79], v[68:71], v[172:175], v[76:79]
	v_mfma_f32_16x16x32_bf16 v[72:75], v[148:151], v[172:175], v[72:75]
	v_mfma_f32_16x16x32_bf16 v[52:55], v[68:71], v[180:183], v[52:55]
	v_mfma_f32_16x16x32_bf16 v[48:51], v[148:151], v[180:183], v[48:51]
	v_mfma_f32_16x16x32_bf16 v[28:31], v[68:71], v[222:225], v[28:31]
	v_mfma_f32_16x16x32_bf16 v[24:27], v[148:151], v[222:225], v[24:27]
	v_mfma_f32_16x16x32_bf16 v[12:15], v[68:71], v[230:233], v[12:15]
	v_mfma_f32_16x16x32_bf16 v[8:11], v[148:151], v[230:233], v[8:11]
	s_setprio 0
	s_setprio 1
	v_mfma_f32_16x16x32_bf16 v[56:59], v[152:155], v[168:171], v[56:59]
	v_mfma_f32_16x16x32_bf16 v[68:71], v[156:159], v[172:175], v[56:59]
	v_mfma_f32_16x16x32_bf16 v[56:59], v[160:163], v[168:171], v[60:63]
	v_mfma_f32_16x16x32_bf16 v[36:39], v[152:155], v[176:179], v[36:39]
	v_mfma_f32_16x16x32_bf16 v[32:35], v[160:163], v[176:179], v[32:35]
	v_mfma_f32_16x16x32_bf16 v[20:23], v[152:155], v[218:221], v[20:23]
	v_mfma_f32_16x16x32_bf16 v[16:19], v[160:163], v[218:221], v[16:19]
	v_mfma_f32_16x16x32_bf16 v[4:7], v[152:155], v[226:229], v[4:7]
	v_mfma_f32_16x16x32_bf16 v[0:3], v[160:163], v[226:229], v[0:3]
	v_mfma_f32_16x16x32_bf16 v[64:67], v[164:167], v[172:175], v[56:59]
	v_mfma_f32_16x16x32_bf16 v[36:39], v[156:159], v[180:183], v[36:39]
	v_mfma_f32_16x16x32_bf16 v[32:35], v[164:167], v[180:183], v[32:35]
	v_mfma_f32_16x16x32_bf16 v[20:23], v[156:159], v[222:225], v[20:23]
	v_mfma_f32_16x16x32_bf16 v[16:19], v[164:167], v[222:225], v[16:19]
	v_mfma_f32_16x16x32_bf16 v[4:7], v[156:159], v[230:233], v[4:7]
	v_mfma_f32_16x16x32_bf16 v[0:3], v[164:167], v[230:233], v[0:3]

.LBB0_961:
	v_lshlrev_b32_e32 v218, 5, v236
	s_lshl_b32 s7, s66, 10
	s_lshl_b32 s8, s77, 2
	s_add_i32 s7, s7, s8
	v_lshlrev_b32_e32 v219, 12, v235
	v_add_u32_e32 v218, s7, v218
	v_lshlrev_b32_e32 v222, 6, v235
	v_lshl_add_u32 v222, v236, 10, v222
	v_add_u32_e32 v219, v219, v218
	s_lshl_b32 s24, s6, 8
	s_add_i32 s24, s24, s76
	s_cmp_eq_u32 s84, 2
	s_cbranch_scc0 .Lepo_full_rows
	s_cmp_eq_u32 s79, 0x100
	s_cbranch_scc0 .Lepo_full_rows
	s_and_b32 s8, s2, 1
	s_lshl_b32 s8, s8, 7
	s_add_i32 s24, s24, s8
.Lepo_full_rows:
	s_lshl_b32 s10, s24, 12
	s_add_u32 s10, s20, s10
	s_addc_u32 s11, s21, 0
	s_lshl_b32 s98, s24, 11
	s_add_i32 s98, s98, 0x2800000
	s_add_u32 s98, s58, s98
	s_addc_u32 s99, s59, 0
	v_lshrrev_b32_e32 v220, 1, v219
	s_cmp_eq_u32 s84, 2
	s_cbranch_scc0 .Lepo_not_half
	s_cmp_eq_u32 s79, 0x100
	s_cbranch_scc1 .Lepo_half
.Lepo_not_half:
	s_cmp_lt_i32 s6, 32
	s_cbranch_scc1 .Lepo_ctx
	s_cmp_lt_i32 s66, 2
	s_cbranch_scc1 .Lepo_per
.Lepo_pec:
	s_lshl_b32 s8, s66, 4
	s_lshl_b32 s9, s75, 2
	s_add_i32 s8, s8, s9
	s_lshl_b32 s9, s24, 6
	s_add_i32 s8, s8, s9
	s_add_i32 s8, s8, 0xea9a000
	s_add_u32 s66, s58, s8
	s_addc_u32 s67, s59, 0
	s_sub_i32 s8, s6, 32
	s_ashr_i32 s8, s8, 3
	s_add_i32 s8, s8, 1
	s_mul_i32 s8, s8, 0x6000
	s_add_i32 s8, s8, 0xe802000
	s_add_u32 s8, s58, s8
	s_addc_u32 s9, s59, 0
	global_load_dwordx4 v[60:63], v218, s[8:9] offset:0
	global_load_dwordx4 v[56:59], v218, s[8:9] offset:16
	global_load_dwordx4 v[44:47], v218, s[8:9] offset:512
	global_load_dwordx4 v[40:43], v218, s[8:9] offset:528
	s_add_u32 s8, s8, 0x2000
	s_addc_u32 s9, s9, 0
	global_load_dwordx4 v[144:147], v218, s[8:9] offset:0
	global_load_dwordx4 v[148:151], v218, s[8:9] offset:16
	global_load_dwordx4 v[152:155], v218, s[8:9] offset:512
	global_load_dwordx4 v[156:159], v218, s[8:9] offset:528
	global_load_dwordx4 v[160:163], v218, s[18:19] offset:0
	global_load_dwordx4 v[164:167], v218, s[18:19] offset:16
	global_load_dwordx4 v[168:171], v218, s[18:19] offset:512
	global_load_dwordx4 v[172:175], v218, s[18:19] offset:528
	s_sub_i32 s8, s24, 0x2000
	s_lshl_b32 s8, s8, 12
	s_add_u32 s8, s14, s8
	s_addc_u32 s9, s15, 0
	s_add_u32 s100, s58, 0xe8fa000
	s_addc_u32 s101, s59, 0
	v_lshlrev_b32_e32 v221, 11, v235
	v_add_u32_e32 v221, v221, v218
	v_add_u32_e32 v221, 0xfffff800, v221
	global_load_dwordx4 v[176:179], v219, s[8:9] offset:0
	global_load_dwordx4 v[180:183], v219, s[8:9] offset:16
	global_load_dwordx4 v[224:227], v221, s[100:101] offset:0
	global_load_dwordx4 v[228:231], v221, s[100:101] offset:16
	s_waitcnt vmcnt(4)
	v_pk_add_f32 v[144:145], v[144:145], 1.0 op_sel_hi:[1,0]
	v_pk_add_f32 v[146:147], v[146:147], 1.0 op_sel_hi:[1,0]
	v_pk_add_f32 v[148:149], v[148:149], 1.0 op_sel_hi:[1,0]
	v_pk_add_f32 v[150:151], v[150:151], 1.0 op_sel_hi:[1,0]
	v_pk_add_f32 v[152:153], v[152:153], 1.0 op_sel_hi:[1,0]
	v_pk_add_f32 v[154:155], v[154:155], 1.0 op_sel_hi:[1,0]
	v_pk_add_f32 v[156:157], v[156:157], 1.0 op_sel_hi:[1,0]
	v_pk_add_f32 v[158:159], v[158:159], 1.0 op_sel_hi:[1,0]
	v_pk_mul_f32 v[144:145], v[160:161], v[144:145]
	v_pk_mul_f32 v[146:147], v[162:163], v[146:147]
	v_pk_mul_f32 v[148:149], v[164:165], v[148:149]
	v_pk_mul_f32 v[150:151], v[166:167], v[150:151]
	v_pk_mul_f32 v[152:153], v[168:169], v[152:153]
	v_pk_mul_f32 v[154:155], v[170:171], v[154:155]
	v_pk_mul_f32 v[156:157], v[172:173], v[156:157]
	v_pk_mul_f32 v[158:159], v[174:175], v[158:159]
	global_load_dwordx4 v[242:245], v219, s[8:9] offset:512
	global_load_dwordx4 v[246:249], v219, s[8:9] offset:528
	global_load_dwordx4 v[160:163], v221, s[100:101] offset:512
	global_load_dwordx4 v[164:167], v221, s[100:101] offset:528
	s_waitcnt vmcnt(4)
	v_pk_add_f32 v[176:177], v[176:177], v[224:225]
	v_pk_add_f32 v[178:179], v[178:179], v[226:227]
	v_pk_add_f32 v[180:181], v[180:181], v[228:229]
	v_pk_add_f32 v[182:183], v[182:183], v[230:231]
	v_pk_fma_f32 v[140:141], v[140:141], v[60:61], v[176:177]
	v_pk_fma_f32 v[142:143], v[142:143], v[62:63], v[178:179]
	v_pk_fma_f32 v[136:137], v[136:137], v[56:57], v[180:181]
	v_pk_fma_f32 v[138:139], v[138:139], v[58:59], v[182:183]
	global_store_dwordx4 v219, v[140:143], s[10:11] offset:0
	global_store_dwordx4 v219, v[136:139], s[10:11] offset:16
	v_mul_f32_e32 v198, v140, v140
	v_fmac_f32_e32 v198, v141, v141
	v_fmac_f32_e32 v198, v142, v142
	v_fmac_f32_e32 v198, v143, v143
	v_fmac_f32_e32 v198, v136, v136
	v_fmac_f32_e32 v198, v137, v137
	v_fmac_f32_e32 v198, v138, v138
	v_fmac_f32_e32 v198, v139, v139
	v_pk_mul_f32 v[176:177], v[144:145], v[140:141]
	v_pk_mul_f32 v[178:179], v[146:147], v[142:143]
	v_pk_mul_f32 v[180:181], v[148:149], v[136:137]
	v_pk_mul_f32 v[182:183], v[150:151], v[138:139]
	v_cvt_pk_bf16_f32 v176, v176, v177
	v_cvt_pk_bf16_f32 v177, v178, v179
	v_cvt_pk_bf16_f32 v178, v180, v181
	v_cvt_pk_bf16_f32 v179, v182, v183
	global_store_dwordx4 v220, v[176:179], s[98:99] offset:0
	s_add_u32 s8, s8, 0x10000
	s_addc_u32 s9, s9, 0
	s_add_u32 s100, s100, 0x8000
	s_addc_u32 s101, s101, 0
	global_load_dwordx4 v[168:171], v219, s[8:9] offset:0
	global_load_dwordx4 v[172:175], v219, s[8:9] offset:16
	global_load_dwordx4 v[180:183], v221, s[100:101] offset:0
	global_load_dwordx4 v[224:227], v221, s[100:101] offset:16
	global_load_dwordx4 v[228:231], v219, s[8:9] offset:512
	global_load_dwordx4 v[140:143], v219, s[8:9] offset:528
	global_load_dwordx4 v[136:139], v221, s[100:101] offset:512
	global_load_dwordx4 v[176:179], v221, s[100:101] offset:528
	s_waitcnt vmcnt(11)
	v_pk_add_f32 v[242:243], v[242:243], v[160:161]
	v_pk_add_f32 v[244:245], v[244:245], v[162:163]
	v_pk_add_f32 v[246:247], v[246:247], v[164:165]
	v_pk_add_f32 v[248:249], v[248:249], v[166:167]
	v_pk_fma_f32 v[132:133], v[132:133], v[44:45], v[242:243]
	v_pk_fma_f32 v[134:135], v[134:135], v[46:47], v[244:245]
	v_pk_fma_f32 v[128:129], v[128:129], v[40:41], v[246:247]
	v_pk_fma_f32 v[130:131], v[130:131], v[42:43], v[248:249]
	global_store_dwordx4 v219, v[132:135], s[10:11] offset:512
	global_store_dwordx4 v219, v[128:131], s[10:11] offset:528
	v_fmac_f32_e32 v198, v132, v132
	v_fmac_f32_e32 v198, v133, v133
	v_fmac_f32_e32 v198, v134, v134
	v_fmac_f32_e32 v198, v135, v135
	v_fmac_f32_e32 v198, v128, v128
	v_fmac_f32_e32 v198, v129, v129
	v_fmac_f32_e32 v198, v130, v130
	v_fmac_f32_e32 v198, v131, v131
	v_pk_mul_f32 v[242:243], v[152:153], v[132:133]
	v_pk_mul_f32 v[244:245], v[154:155], v[134:135]
	v_pk_mul_f32 v[246:247], v[156:157], v[128:129]
	v_pk_mul_f32 v[248:249], v[158:159], v[130:131]
	v_cvt_pk_bf16_f32 v242, v242, v243
	v_cvt_pk_bf16_f32 v243, v244, v245
	v_cvt_pk_bf16_f32 v244, v246, v247
	v_cvt_pk_bf16_f32 v245, v248, v249
	global_store_dwordx4 v220, v[242:245], s[98:99] offset:256
	v_mov_b32_e32 v240, v198
	s_nop 1
	v_permlane16_swap_b32_e32 v198, v240
	v_add_f32_e32 v240, v198, v240
	v_mov_b32_e32 v241, v240
	s_nop 1
	v_permlane32_swap_b32_e32 v240, v241
	v_add_f32_e32 v240, v240, v241
	v_mov_b32_e32 v233, v240
	s_add_u32 s8, s8, 0x10000
	s_addc_u32 s9, s9, 0
	s_add_u32 s100, s100, 0x8000
	s_addc_u32 s101, s101, 0
	global_load_dwordx4 v[246:249], v219, s[8:9] offset:0
	global_load_dwordx4 v[160:163], v219, s[8:9] offset:16
	global_load_dwordx4 v[164:167], v221, s[100:101] offset:0
	global_load_dwordx4 v[132:135], v221, s[100:101] offset:16
	s_waitcnt vmcnt(11)
	s_add_u32 s10, s10, 0x10000
	s_addc_u32 s11, s11, 0
	s_add_u32 s98, s98, 0x8000
	s_addc_u32 s99, s99, 0
	s_add_u32 s66, s66, 0x400
	s_addc_u32 s67, s67, 0
	v_pk_add_f32 v[168:169], v[168:169], v[180:181]
	v_pk_add_f32 v[170:171], v[170:171], v[182:183]
	v_pk_add_f32 v[172:173], v[172:173], v[224:225]
	v_pk_add_f32 v[174:175], v[174:175], v[226:227]
	v_pk_fma_f32 v[124:125], v[124:125], v[60:61], v[168:169]
	v_pk_fma_f32 v[126:127], v[126:127], v[62:63], v[170:171]
	v_pk_fma_f32 v[120:121], v[120:121], v[56:57], v[172:173]
	v_pk_fma_f32 v[122:123], v[122:123], v[58:59], v[174:175]
	global_store_dwordx4 v219, v[124:127], s[10:11] offset:0
	global_store_dwordx4 v219, v[120:123], s[10:11] offset:16
	v_mul_f32_e32 v198, v124, v124
	v_fmac_f32_e32 v198, v125, v125
	v_fmac_f32_e32 v198, v126, v126
	v_fmac_f32_e32 v198, v127, v127
	v_fmac_f32_e32 v198, v120, v120
	v_fmac_f32_e32 v198, v121, v121
	v_fmac_f32_e32 v198, v122, v122
	v_fmac_f32_e32 v198, v123, v123
	v_pk_mul_f32 v[168:169], v[144:145], v[124:125]
	v_pk_mul_f32 v[170:171], v[146:147], v[126:127]
	v_pk_mul_f32 v[172:173], v[148:149], v[120:121]
	v_pk_mul_f32 v[174:175], v[150:151], v[122:123]
	v_cvt_pk_bf16_f32 v168, v168, v169
	v_cvt_pk_bf16_f32 v169, v170, v171
	v_cvt_pk_bf16_f32 v170, v172, v173
	v_cvt_pk_bf16_f32 v171, v174, v175
	global_store_dwordx4 v220, v[168:171], s[98:99] offset:0
	global_load_dwordx4 v[128:131], v219, s[8:9] offset:512
	global_load_dwordx4 v[242:245], v219, s[8:9] offset:528
	global_load_dwordx4 v[172:175], v221, s[100:101] offset:512
	global_load_dwordx4 v[180:183], v221, s[100:101] offset:528
	s_add_u32 s8, s8, 0x10000
	s_addc_u32 s9, s9, 0
	s_add_u32 s100, s100, 0x8000
	s_addc_u32 s101, s101, 0
	global_load_dwordx4 v[224:227], v219, s[8:9] offset:0
	global_load_dwordx4 v[124:127], v219, s[8:9] offset:16
	global_load_dwordx4 v[120:123], v221, s[100:101] offset:0
	global_load_dwordx4 v[168:171], v221, s[100:101] offset:16
	s_waitcnt vmcnt(18)
	v_pk_add_f32 v[228:229], v[228:229], v[136:137]
	v_pk_add_f32 v[230:231], v[230:231], v[138:139]
	v_pk_add_f32 v[140:141], v[140:141], v[176:177]
	v_pk_add_f32 v[142:143], v[142:143], v[178:179]
	v_pk_fma_f32 v[116:117], v[116:117], v[44:45], v[228:229]
	v_pk_fma_f32 v[118:119], v[118:119], v[46:47], v[230:231]
	v_pk_fma_f32 v[112:113], v[112:113], v[40:41], v[140:141]
	v_pk_fma_f32 v[114:115], v[114:115], v[42:43], v[142:143]
	global_store_dwordx4 v219, v[116:119], s[10:11] offset:512
	global_store_dwordx4 v219, v[112:115], s[10:11] offset:528
	v_fmac_f32_e32 v198, v116, v116
	v_fmac_f32_e32 v198, v117, v117
	v_fmac_f32_e32 v198, v118, v118
	v_fmac_f32_e32 v198, v119, v119
	v_fmac_f32_e32 v198, v112, v112
	v_fmac_f32_e32 v198, v113, v113
	v_fmac_f32_e32 v198, v114, v114
	v_fmac_f32_e32 v198, v115, v115
	v_pk_mul_f32 v[228:229], v[152:153], v[116:117]
	v_pk_mul_f32 v[230:231], v[154:155], v[118:119]
	v_pk_mul_f32 v[140:141], v[156:157], v[112:113]
	v_pk_mul_f32 v[142:143], v[158:159], v[114:115]
	v_cvt_pk_bf16_f32 v228, v228, v229
	v_cvt_pk_bf16_f32 v229, v230, v231
	v_cvt_pk_bf16_f32 v230, v140, v141
	v_cvt_pk_bf16_f32 v231, v142, v143
	global_store_dwordx4 v220, v[228:231], s[98:99] offset:256
	v_mov_b32_e32 v240, v198
	s_nop 1
	v_permlane16_swap_b32_e32 v198, v240
	v_add_f32_e32 v240, v198, v240
	v_mov_b32_e32 v241, v240
	s_nop 1
	v_permlane32_swap_b32_e32 v240, v241
	v_add_f32_e32 v240, v240, v241
	v_cmp_eq_u32_e64 s[6:7], 1, v236
	s_nop 1
	v_cndmask_b32_e64 v233, v233, v240, s[6:7]
	global_load_dwordx4 v[140:143], v219, s[8:9] offset:512
	global_load_dwordx4 v[136:139], v219, s[8:9] offset:528
	global_load_dwordx4 v[176:179], v221, s[100:101] offset:512
	global_load_dwordx4 v[116:119], v221, s[100:101] offset:528
	s_waitcnt vmcnt(18)
	s_add_u32 s10, s10, 0x10000
	s_addc_u32 s11, s11, 0
	s_add_u32 s98, s98, 0x8000
	s_addc_u32 s99, s99, 0
	s_add_u32 s66, s66, 0x400
	s_addc_u32 s67, s67, 0
	v_pk_add_f32 v[246:247], v[246:247], v[164:165]
	v_pk_add_f32 v[248:249], v[248:249], v[166:167]
	v_pk_add_f32 v[160:161], v[160:161], v[132:133]
	v_pk_add_f32 v[162:163], v[162:163], v[134:135]
	v_pk_fma_f32 v[108:109], v[108:109], v[60:61], v[246:247]
	v_pk_fma_f32 v[110:111], v[110:111], v[62:63], v[248:249]
	v_pk_fma_f32 v[104:105], v[104:105], v[56:57], v[160:161]
	v_pk_fma_f32 v[106:107], v[106:107], v[58:59], v[162:163]
	global_store_dwordx4 v219, v[108:111], s[10:11] offset:0
	global_store_dwordx4 v219, v[104:107], s[10:11] offset:16
	v_mul_f32_e32 v198, v108, v108
	v_fmac_f32_e32 v198, v109, v109
	v_fmac_f32_e32 v198, v110, v110
	v_fmac_f32_e32 v198, v111, v111
	v_fmac_f32_e32 v198, v104, v104
	v_fmac_f32_e32 v198, v105, v105
	v_fmac_f32_e32 v198, v106, v106
	v_fmac_f32_e32 v198, v107, v107
	v_pk_mul_f32 v[246:247], v[144:145], v[108:109]
	v_pk_mul_f32 v[248:249], v[146:147], v[110:111]
	v_pk_mul_f32 v[160:161], v[148:149], v[104:105]
	v_pk_mul_f32 v[162:163], v[150:151], v[106:107]
	v_cvt_pk_bf16_f32 v246, v246, v247
	v_cvt_pk_bf16_f32 v247, v248, v249
	v_cvt_pk_bf16_f32 v248, v160, v161
	v_cvt_pk_bf16_f32 v249, v162, v163
	global_store_dwordx4 v220, v[246:249], s[98:99] offset:0
	s_add_u32 s8, s8, 0x50000
	s_addc_u32 s9, s9, 0
	s_sub_u32 s100, s100, 0x18000
	s_subb_u32 s101, s101, 0
	global_load_dwordx4 v[112:115], v219, s[8:9] offset:0
	global_load_dwordx4 v[228:231], v219, s[8:9] offset:16
	global_load_dwordx4 v[160:163], v221, s[100:101] offset:0
	global_load_dwordx4 v[164:167], v221, s[100:101] offset:16
	global_load_dwordx4 v[132:135], v219, s[8:9] offset:512
	global_load_dwordx4 v[108:111], v219, s[8:9] offset:528
	global_load_dwordx4 v[104:107], v221, s[100:101] offset:512
	global_load_dwordx4 v[246:249], v221, s[100:101] offset:528
	s_waitcnt vmcnt(22)
	v_pk_add_f32 v[128:129], v[128:129], v[172:173]
	v_pk_add_f32 v[130:131], v[130:131], v[174:175]
	v_pk_add_f32 v[242:243], v[242:243], v[180:181]
	v_pk_add_f32 v[244:245], v[244:245], v[182:183]
	v_pk_fma_f32 v[100:101], v[100:101], v[44:45], v[128:129]
	v_pk_fma_f32 v[102:103], v[102:103], v[46:47], v[130:131]
	v_pk_fma_f32 v[96:97], v[96:97], v[40:41], v[242:243]
	v_pk_fma_f32 v[98:99], v[98:99], v[42:43], v[244:245]
	global_store_dwordx4 v219, v[100:103], s[10:11] offset:512
	global_store_dwordx4 v219, v[96:99], s[10:11] offset:528
	v_fmac_f32_e32 v198, v100, v100
	v_fmac_f32_e32 v198, v101, v101
	v_fmac_f32_e32 v198, v102, v102
	v_fmac_f32_e32 v198, v103, v103
	v_fmac_f32_e32 v198, v96, v96
	v_fmac_f32_e32 v198, v97, v97
	v_fmac_f32_e32 v198, v98, v98
	v_fmac_f32_e32 v198, v99, v99
	v_pk_mul_f32 v[128:129], v[152:153], v[100:101]
	v_pk_mul_f32 v[130:131], v[154:155], v[102:103]
	v_pk_mul_f32 v[242:243], v[156:157], v[96:97]
	v_pk_mul_f32 v[244:245], v[158:159], v[98:99]
	v_cvt_pk_bf16_f32 v128, v128, v129
	v_cvt_pk_bf16_f32 v129, v130, v131
	v_cvt_pk_bf16_f32 v130, v242, v243
	v_cvt_pk_bf16_f32 v131, v244, v245
	global_store_dwordx4 v220, v[128:131], s[98:99] offset:256
	v_mov_b32_e32 v240, v198
	s_nop 1
	v_permlane16_swap_b32_e32 v198, v240
	v_add_f32_e32 v240, v198, v240
	v_mov_b32_e32 v241, v240
	s_nop 1
	v_permlane32_swap_b32_e32 v240, v241
	v_add_f32_e32 v240, v240, v241
	v_cmp_eq_u32_e64 s[6:7], 2, v236
	s_nop 1
	v_cndmask_b32_e64 v233, v233, v240, s[6:7]
	s_add_u32 s8, s8, 0x10000
	s_addc_u32 s9, s9, 0
	s_add_u32 s100, s100, 0x8000
	s_addc_u32 s101, s101, 0
	global_load_dwordx4 v[242:245], v219, s[8:9] offset:0
	global_load_dwordx4 v[172:175], v219, s[8:9] offset:16
	global_load_dwordx4 v[180:183], v221, s[100:101] offset:0
	global_load_dwordx4 v[100:103], v221, s[100:101] offset:16
	s_waitcnt vmcnt(25)
	s_add_u32 s10, s10, 0x10000
	s_addc_u32 s11, s11, 0
	s_add_u32 s98, s98, 0x8000
	s_addc_u32 s99, s99, 0
	s_add_u32 s66, s66, 0x400
	s_addc_u32 s67, s67, 0
	v_pk_add_f32 v[224:225], v[224:225], v[120:121]
	v_pk_add_f32 v[226:227], v[226:227], v[122:123]
	v_pk_add_f32 v[124:125], v[124:125], v[168:169]
	v_pk_add_f32 v[126:127], v[126:127], v[170:171]
	v_pk_fma_f32 v[92:93], v[92:93], v[60:61], v[224:225]
	v_pk_fma_f32 v[94:95], v[94:95], v[62:63], v[226:227]
	v_pk_fma_f32 v[88:89], v[88:89], v[56:57], v[124:125]
	v_pk_fma_f32 v[90:91], v[90:91], v[58:59], v[126:127]
	global_store_dwordx4 v219, v[92:95], s[10:11] offset:0
	global_store_dwordx4 v219, v[88:91], s[10:11] offset:16
	v_mul_f32_e32 v198, v92, v92
	v_fmac_f32_e32 v198, v93, v93
	v_fmac_f32_e32 v198, v94, v94
	v_fmac_f32_e32 v198, v95, v95
	v_fmac_f32_e32 v198, v88, v88
	v_fmac_f32_e32 v198, v89, v89
	v_fmac_f32_e32 v198, v90, v90
	v_fmac_f32_e32 v198, v91, v91
	v_pk_mul_f32 v[224:225], v[144:145], v[92:93]
	v_pk_mul_f32 v[226:227], v[146:147], v[94:95]
	v_pk_mul_f32 v[124:125], v[148:149], v[88:89]
	v_pk_mul_f32 v[126:127], v[150:151], v[90:91]
	v_cvt_pk_bf16_f32 v224, v224, v225
	v_cvt_pk_bf16_f32 v225, v226, v227
	v_cvt_pk_bf16_f32 v226, v124, v125
	v_cvt_pk_bf16_f32 v227, v126, v127
	global_store_dwordx4 v220, v[224:227], s[98:99] offset:0
	global_load_dwordx4 v[96:99], v219, s[8:9] offset:512
	global_load_dwordx4 v[128:131], v219, s[8:9] offset:528
	global_load_dwordx4 v[124:127], v221, s[100:101] offset:512
	global_load_dwordx4 v[120:123], v221, s[100:101] offset:528
	s_add_u32 s8, s8, 0x10000
	s_addc_u32 s9, s9, 0
	s_add_u32 s100, s100, 0x8000
	s_addc_u32 s101, s101, 0
	global_load_dwordx4 v[168:171], v219, s[8:9] offset:0
	global_load_dwordx4 v[92:95], v219, s[8:9] offset:16
	global_load_dwordx4 v[88:91], v221, s[100:101] offset:0
	global_load_dwordx4 v[224:227], v221, s[100:101] offset:16
	s_waitcnt vmcnt(29)
	v_pk_add_f32 v[140:141], v[140:141], v[176:177]
	v_pk_add_f32 v[142:143], v[142:143], v[178:179]
	v_pk_add_f32 v[136:137], v[136:137], v[116:117]
	v_pk_add_f32 v[138:139], v[138:139], v[118:119]
	v_pk_fma_f32 v[84:85], v[84:85], v[44:45], v[140:141]
	v_pk_fma_f32 v[86:87], v[86:87], v[46:47], v[142:143]
	v_pk_fma_f32 v[80:81], v[80:81], v[40:41], v[136:137]
	v_pk_fma_f32 v[82:83], v[82:83], v[42:43], v[138:139]
	global_store_dwordx4 v219, v[84:87], s[10:11] offset:512
	global_store_dwordx4 v219, v[80:83], s[10:11] offset:528
	v_fmac_f32_e32 v198, v84, v84
	v_fmac_f32_e32 v198, v85, v85
	v_fmac_f32_e32 v198, v86, v86
	v_fmac_f32_e32 v198, v87, v87
	v_fmac_f32_e32 v198, v80, v80
	v_fmac_f32_e32 v198, v81, v81
	v_fmac_f32_e32 v198, v82, v82
	v_fmac_f32_e32 v198, v83, v83
	v_pk_mul_f32 v[140:141], v[152:153], v[84:85]
	v_pk_mul_f32 v[142:143], v[154:155], v[86:87]
	v_pk_mul_f32 v[136:137], v[156:157], v[80:81]
	v_pk_mul_f32 v[138:139], v[158:159], v[82:83]
	v_cvt_pk_bf16_f32 v140, v140, v141
	v_cvt_pk_bf16_f32 v141, v142, v143
	v_cvt_pk_bf16_f32 v142, v136, v137
	v_cvt_pk_bf16_f32 v143, v138, v139
	global_store_dwordx4 v220, v[140:143], s[98:99] offset:256
	v_mov_b32_e32 v240, v198
	s_nop 1
	v_permlane16_swap_b32_e32 v198, v240
	v_add_f32_e32 v240, v198, v240
	v_mov_b32_e32 v241, v240
	s_nop 1
	v_permlane32_swap_b32_e32 v240, v241
	v_add_f32_e32 v240, v240, v241
	v_cmp_eq_u32_e64 s[6:7], 3, v236
	s_nop 1
	v_cndmask_b32_e64 v233, v233, v240, s[6:7]
	global_store_dword v222, v233, s[66:67] offset:-3072
	global_load_dwordx4 v[136:139], v219, s[8:9] offset:512
	global_load_dwordx4 v[176:179], v219, s[8:9] offset:528
	global_load_dwordx4 v[116:119], v221, s[100:101] offset:512
	global_load_dwordx4 v[84:87], v221, s[100:101] offset:528
	s_waitcnt vmcnt(30)
	s_add_u32 s10, s10, 0x50000
	s_addc_u32 s11, s11, 0
	s_add_u32 s98, s98, 0x28000
	s_addc_u32 s99, s99, 0
	s_add_u32 s66, s66, 0x1400
	s_addc_u32 s67, s67, 0
	v_pk_add_f32 v[112:113], v[112:113], v[160:161]
	v_pk_add_f32 v[114:115], v[114:115], v[162:163]
	v_pk_add_f32 v[228:229], v[228:229], v[164:165]
	v_pk_add_f32 v[230:231], v[230:231], v[166:167]
	v_pk_fma_f32 v[76:77], v[76:77], v[60:61], v[112:113]
	v_pk_fma_f32 v[78:79], v[78:79], v[62:63], v[114:115]
	v_pk_fma_f32 v[72:73], v[72:73], v[56:57], v[228:229]
	v_pk_fma_f32 v[74:75], v[74:75], v[58:59], v[230:231]
	global_store_dwordx4 v219, v[76:79], s[10:11] offset:0
	global_store_dwordx4 v219, v[72:75], s[10:11] offset:16
	v_mul_f32_e32 v198, v76, v76
	v_fmac_f32_e32 v198, v77, v77
	v_fmac_f32_e32 v198, v78, v78
	v_fmac_f32_e32 v198, v79, v79
	v_fmac_f32_e32 v198, v72, v72
	v_fmac_f32_e32 v198, v73, v73
	v_fmac_f32_e32 v198, v74, v74
	v_fmac_f32_e32 v198, v75, v75
	v_pk_mul_f32 v[112:113], v[144:145], v[76:77]
	v_pk_mul_f32 v[114:115], v[146:147], v[78:79]
	v_pk_mul_f32 v[228:229], v[148:149], v[72:73]
	v_pk_mul_f32 v[230:231], v[150:151], v[74:75]
	v_cvt_pk_bf16_f32 v112, v112, v113
	v_cvt_pk_bf16_f32 v113, v114, v115
	v_cvt_pk_bf16_f32 v114, v228, v229
	v_cvt_pk_bf16_f32 v115, v230, v231
	global_store_dwordx4 v220, v[112:115], s[98:99] offset:0
	s_add_u32 s8, s8, 0x10000
	s_addc_u32 s9, s9, 0
	s_add_u32 s100, s100, 0x8000
	s_addc_u32 s101, s101, 0
	global_load_dwordx4 v[80:83], v219, s[8:9] offset:0
	global_load_dwordx4 v[140:143], v219, s[8:9] offset:16
	global_load_dwordx4 v[228:231], v221, s[100:101] offset:0
	global_load_dwordx4 v[160:163], v221, s[100:101] offset:16
	global_load_dwordx4 v[164:167], v219, s[8:9] offset:512
	global_load_dwordx4 v[76:79], v219, s[8:9] offset:528
	global_load_dwordx4 v[72:75], v221, s[100:101] offset:512
	global_load_dwordx4 v[112:115], v221, s[100:101] offset:528
	s_waitcnt vmcnt(37)
	v_pk_add_f32 v[132:133], v[132:133], v[104:105]
	v_pk_add_f32 v[134:135], v[134:135], v[106:107]
	v_pk_add_f32 v[108:109], v[108:109], v[246:247]
	v_pk_add_f32 v[110:111], v[110:111], v[248:249]
	v_pk_fma_f32 v[68:69], v[68:69], v[44:45], v[132:133]
	v_pk_fma_f32 v[70:71], v[70:71], v[46:47], v[134:135]
	v_pk_fma_f32 v[64:65], v[64:65], v[40:41], v[108:109]
	v_pk_fma_f32 v[66:67], v[66:67], v[42:43], v[110:111]
	global_store_dwordx4 v219, v[68:71], s[10:11] offset:512
	global_store_dwordx4 v219, v[64:67], s[10:11] offset:528
	v_fmac_f32_e32 v198, v68, v68
	v_fmac_f32_e32 v198, v69, v69
	v_fmac_f32_e32 v198, v70, v70
	v_fmac_f32_e32 v198, v71, v71
	v_fmac_f32_e32 v198, v64, v64
	v_fmac_f32_e32 v198, v65, v65
	v_fmac_f32_e32 v198, v66, v66
	v_fmac_f32_e32 v198, v67, v67
	v_pk_mul_f32 v[132:133], v[152:153], v[68:69]
	v_pk_mul_f32 v[134:135], v[154:155], v[70:71]
	v_pk_mul_f32 v[108:109], v[156:157], v[64:65]
	v_pk_mul_f32 v[110:111], v[158:159], v[66:67]
	v_cvt_pk_bf16_f32 v132, v132, v133
	v_cvt_pk_bf16_f32 v133, v134, v135
	v_cvt_pk_bf16_f32 v134, v108, v109
	v_cvt_pk_bf16_f32 v135, v110, v111
	global_store_dwordx4 v220, v[132:135], s[98:99] offset:256
	v_mov_b32_e32 v240, v198
	s_nop 1
	v_permlane16_swap_b32_e32 v198, v240
	v_add_f32_e32 v240, v198, v240
	v_mov_b32_e32 v241, v240
	s_nop 1
	v_permlane32_swap_b32_e32 v240, v241
	v_add_f32_e32 v240, v240, v241
	v_mov_b32_e32 v233, v240
	s_waitcnt vmcnt(33)
	s_add_u32 s10, s10, 0x10000
	s_addc_u32 s11, s11, 0
	s_add_u32 s98, s98, 0x8000
	s_addc_u32 s99, s99, 0
	s_add_u32 s66, s66, 0x400
	s_addc_u32 s67, s67, 0
	v_pk_add_f32 v[242:243], v[242:243], v[180:181]
	v_pk_add_f32 v[244:245], v[244:245], v[182:183]
	v_pk_add_f32 v[172:173], v[172:173], v[100:101]
	v_pk_add_f32 v[174:175], v[174:175], v[102:103]
	v_pk_fma_f32 v[52:53], v[52:53], v[60:61], v[242:243]
	v_pk_fma_f32 v[54:55], v[54:55], v[62:63], v[244:245]
	v_pk_fma_f32 v[48:49], v[48:49], v[56:57], v[172:173]
	v_pk_fma_f32 v[50:51], v[50:51], v[58:59], v[174:175]
	global_store_dwordx4 v219, v[52:55], s[10:11] offset:0
	global_store_dwordx4 v219, v[48:51], s[10:11] offset:16
	v_mul_f32_e32 v198, v52, v52
	v_fmac_f32_e32 v198, v53, v53
	v_fmac_f32_e32 v198, v54, v54
	v_fmac_f32_e32 v198, v55, v55
	v_fmac_f32_e32 v198, v48, v48
	v_fmac_f32_e32 v198, v49, v49
	v_fmac_f32_e32 v198, v50, v50
	v_fmac_f32_e32 v198, v51, v51
	v_pk_mul_f32 v[242:243], v[144:145], v[52:53]
	v_pk_mul_f32 v[244:245], v[146:147], v[54:55]
	v_pk_mul_f32 v[172:173], v[148:149], v[48:49]
	v_pk_mul_f32 v[174:175], v[150:151], v[50:51]
	v_cvt_pk_bf16_f32 v242, v242, v243
	v_cvt_pk_bf16_f32 v243, v244, v245
	v_cvt_pk_bf16_f32 v244, v172, v173
	v_cvt_pk_bf16_f32 v245, v174, v175
	global_store_dwordx4 v220, v[242:245], s[98:99] offset:0
	s_waitcnt vmcnt(29)
	v_pk_add_f32 v[96:97], v[96:97], v[124:125]
	v_pk_add_f32 v[98:99], v[98:99], v[126:127]
	v_pk_add_f32 v[128:129], v[128:129], v[120:121]
	v_pk_add_f32 v[130:131], v[130:131], v[122:123]
	v_pk_fma_f32 v[36:37], v[36:37], v[44:45], v[96:97]
	v_pk_fma_f32 v[38:39], v[38:39], v[46:47], v[98:99]
	v_pk_fma_f32 v[32:33], v[32:33], v[40:41], v[128:129]
	v_pk_fma_f32 v[34:35], v[34:35], v[42:43], v[130:131]
	global_store_dwordx4 v219, v[36:39], s[10:11] offset:512
	global_store_dwordx4 v219, v[32:35], s[10:11] offset:528
	v_fmac_f32_e32 v198, v36, v36
	v_fmac_f32_e32 v198, v37, v37
	v_fmac_f32_e32 v198, v38, v38
	v_fmac_f32_e32 v198, v39, v39
	v_fmac_f32_e32 v198, v32, v32
	v_fmac_f32_e32 v198, v33, v33
	v_fmac_f32_e32 v198, v34, v34
	v_fmac_f32_e32 v198, v35, v35
	v_pk_mul_f32 v[96:97], v[152:153], v[36:37]
	v_pk_mul_f32 v[98:99], v[154:155], v[38:39]
	v_pk_mul_f32 v[128:129], v[156:157], v[32:33]
	v_pk_mul_f32 v[130:131], v[158:159], v[34:35]
	v_cvt_pk_bf16_f32 v96, v96, v97
	v_cvt_pk_bf16_f32 v97, v98, v99
	v_cvt_pk_bf16_f32 v98, v128, v129
	v_cvt_pk_bf16_f32 v99, v130, v131
	global_store_dwordx4 v220, v[96:99], s[98:99] offset:256
	v_mov_b32_e32 v240, v198
	s_nop 1
	v_permlane16_swap_b32_e32 v198, v240
	v_add_f32_e32 v240, v198, v240
	v_mov_b32_e32 v241, v240
	s_nop 1
	v_permlane32_swap_b32_e32 v240, v241
	v_add_f32_e32 v240, v240, v241
	v_cmp_eq_u32_e64 s[6:7], 1, v236
	s_nop 1
	v_cndmask_b32_e64 v233, v233, v240, s[6:7]
	s_waitcnt vmcnt(28)
	s_add_u32 s10, s10, 0x10000
	s_addc_u32 s11, s11, 0
	s_add_u32 s98, s98, 0x8000
	s_addc_u32 s99, s99, 0
	s_add_u32 s66, s66, 0x400
	s_addc_u32 s67, s67, 0
	v_pk_add_f32 v[168:169], v[168:169], v[88:89]
	v_pk_add_f32 v[170:171], v[170:171], v[90:91]
	v_pk_add_f32 v[92:93], v[92:93], v[224:225]
	v_pk_add_f32 v[94:95], v[94:95], v[226:227]
	v_pk_fma_f32 v[28:29], v[28:29], v[60:61], v[168:169]
	v_pk_fma_f32 v[30:31], v[30:31], v[62:63], v[170:171]
	v_pk_fma_f32 v[24:25], v[24:25], v[56:57], v[92:93]
	v_pk_fma_f32 v[26:27], v[26:27], v[58:59], v[94:95]
	global_store_dwordx4 v219, v[28:31], s[10:11] offset:0
	global_store_dwordx4 v219, v[24:27], s[10:11] offset:16
	v_mul_f32_e32 v198, v28, v28
	v_fmac_f32_e32 v198, v29, v29
	v_fmac_f32_e32 v198, v30, v30
	v_fmac_f32_e32 v198, v31, v31
	v_fmac_f32_e32 v198, v24, v24
	v_fmac_f32_e32 v198, v25, v25
	v_fmac_f32_e32 v198, v26, v26
	v_fmac_f32_e32 v198, v27, v27
	v_pk_mul_f32 v[168:169], v[144:145], v[28:29]
	v_pk_mul_f32 v[170:171], v[146:147], v[30:31]
	v_pk_mul_f32 v[92:93], v[148:149], v[24:25]
	v_pk_mul_f32 v[94:95], v[150:151], v[26:27]
	v_cvt_pk_bf16_f32 v168, v168, v169
	v_cvt_pk_bf16_f32 v169, v170, v171
	v_cvt_pk_bf16_f32 v170, v92, v93
	v_cvt_pk_bf16_f32 v171, v94, v95
	global_store_dwordx4 v220, v[168:171], s[98:99] offset:0
	s_waitcnt vmcnt(23)
	v_pk_add_f32 v[136:137], v[136:137], v[116:117]
	v_pk_add_f32 v[138:139], v[138:139], v[118:119]
	v_pk_add_f32 v[176:177], v[176:177], v[84:85]
	v_pk_add_f32 v[178:179], v[178:179], v[86:87]
	v_pk_fma_f32 v[20:21], v[20:21], v[44:45], v[136:137]
	v_pk_fma_f32 v[22:23], v[22:23], v[46:47], v[138:139]
	v_pk_fma_f32 v[16:17], v[16:17], v[40:41], v[176:177]
	v_pk_fma_f32 v[18:19], v[18:19], v[42:43], v[178:179]
	global_store_dwordx4 v219, v[20:23], s[10:11] offset:512
	global_store_dwordx4 v219, v[16:19], s[10:11] offset:528
	v_fmac_f32_e32 v198, v20, v20
	v_fmac_f32_e32 v198, v21, v21
	v_fmac_f32_e32 v198, v22, v22
	v_fmac_f32_e32 v198, v23, v23
	v_fmac_f32_e32 v198, v16, v16
	v_fmac_f32_e32 v198, v17, v17
	v_fmac_f32_e32 v198, v18, v18
	v_fmac_f32_e32 v198, v19, v19
	v_pk_mul_f32 v[136:137], v[152:153], v[20:21]
	v_pk_mul_f32 v[138:139], v[154:155], v[22:23]
	v_pk_mul_f32 v[176:177], v[156:157], v[16:17]
	v_pk_mul_f32 v[178:179], v[158:159], v[18:19]
	v_cvt_pk_bf16_f32 v136, v136, v137
	v_cvt_pk_bf16_f32 v137, v138, v139
	v_cvt_pk_bf16_f32 v138, v176, v177
	v_cvt_pk_bf16_f32 v139, v178, v179
	global_store_dwordx4 v220, v[136:139], s[98:99] offset:256
	v_mov_b32_e32 v240, v198
	s_nop 1
	v_permlane16_swap_b32_e32 v198, v240
	v_add_f32_e32 v240, v198, v240
	v_mov_b32_e32 v241, v240
	s_nop 1
	v_permlane32_swap_b32_e32 v240, v241
	v_add_f32_e32 v240, v240, v241
	v_cmp_eq_u32_e64 s[6:7], 2, v236
	s_nop 1
	v_cndmask_b32_e64 v233, v233, v240, s[6:7]
	s_waitcnt vmcnt(19)
	s_add_u32 s10, s10, 0x10000
	s_addc_u32 s11, s11, 0
	s_add_u32 s98, s98, 0x8000
	s_addc_u32 s99, s99, 0
	s_add_u32 s66, s66, 0x400
	s_addc_u32 s67, s67, 0
	v_pk_add_f32 v[80:81], v[80:81], v[228:229]
	v_pk_add_f32 v[82:83], v[82:83], v[230:231]
	v_pk_add_f32 v[140:141], v[140:141], v[160:161]
	v_pk_add_f32 v[142:143], v[142:143], v[162:163]
	v_pk_fma_f32 v[12:13], v[12:13], v[60:61], v[80:81]
	v_pk_fma_f32 v[14:15], v[14:15], v[62:63], v[82:83]
	v_pk_fma_f32 v[8:9], v[8:9], v[56:57], v[140:141]
	v_pk_fma_f32 v[10:11], v[10:11], v[58:59], v[142:143]
	global_store_dwordx4 v219, v[12:15], s[10:11] offset:0
	global_store_dwordx4 v219, v[8:11], s[10:11] offset:16
	v_mul_f32_e32 v198, v12, v12
	v_fmac_f32_e32 v198, v13, v13
	v_fmac_f32_e32 v198, v14, v14
	v_fmac_f32_e32 v198, v15, v15
	v_fmac_f32_e32 v198, v8, v8
	v_fmac_f32_e32 v198, v9, v9
	v_fmac_f32_e32 v198, v10, v10
	v_fmac_f32_e32 v198, v11, v11
	v_pk_mul_f32 v[80:81], v[144:145], v[12:13]
	v_pk_mul_f32 v[82:83], v[146:147], v[14:15]
	v_pk_mul_f32 v[140:141], v[148:149], v[8:9]
	v_pk_mul_f32 v[142:143], v[150:151], v[10:11]
	v_cvt_pk_bf16_f32 v80, v80, v81
	v_cvt_pk_bf16_f32 v81, v82, v83
	v_cvt_pk_bf16_f32 v82, v140, v141
	v_cvt_pk_bf16_f32 v83, v142, v143
	global_store_dwordx4 v220, v[80:83], s[98:99] offset:0
	s_waitcnt vmcnt(18)
	v_pk_add_f32 v[164:165], v[164:165], v[72:73]
	v_pk_add_f32 v[166:167], v[166:167], v[74:75]
	v_pk_add_f32 v[76:77], v[76:77], v[112:113]
	v_pk_add_f32 v[78:79], v[78:79], v[114:115]
	v_pk_fma_f32 v[4:5], v[4:5], v[44:45], v[164:165]
	v_pk_fma_f32 v[6:7], v[6:7], v[46:47], v[166:167]
	v_pk_fma_f32 v[0:1], v[0:1], v[40:41], v[76:77]
	v_pk_fma_f32 v[2:3], v[2:3], v[42:43], v[78:79]
	global_store_dwordx4 v219, v[4:7], s[10:11] offset:512
	global_store_dwordx4 v219, v[0:3], s[10:11] offset:528
	v_fmac_f32_e32 v198, v4, v4
	v_fmac_f32_e32 v198, v5, v5
	v_fmac_f32_e32 v198, v6, v6
	v_fmac_f32_e32 v198, v7, v7
	v_fmac_f32_e32 v198, v0, v0
	v_fmac_f32_e32 v198, v1, v1
	v_fmac_f32_e32 v198, v2, v2
	v_fmac_f32_e32 v198, v3, v3
	v_pk_mul_f32 v[164:165], v[152:153], v[4:5]
	v_pk_mul_f32 v[166:167], v[154:155], v[6:7]
	v_pk_mul_f32 v[76:77], v[156:157], v[0:1]
	v_pk_mul_f32 v[78:79], v[158:159], v[2:3]
	v_cvt_pk_bf16_f32 v164, v164, v165
	v_cvt_pk_bf16_f32 v165, v166, v167
	v_cvt_pk_bf16_f32 v166, v76, v77
	v_cvt_pk_bf16_f32 v167, v78, v79
	global_store_dwordx4 v220, v[164:167], s[98:99] offset:256
	v_mov_b32_e32 v240, v198
	s_nop 1
	v_permlane16_swap_b32_e32 v198, v240
	v_add_f32_e32 v240, v198, v240
	v_mov_b32_e32 v241, v240
	s_nop 1
	v_permlane32_swap_b32_e32 v240, v241
	v_add_f32_e32 v240, v240, v241
	v_cmp_eq_u32_e64 s[6:7], 3, v236
	s_nop 1
	v_cndmask_b32_e64 v233, v233, v240, s[6:7]
	global_store_dword v222, v233, s[66:67] offset:-3072
	s_branch .Lepo_done
